# attention unit-1 finalize and pool-unit stores use plain write-back (followed by more work in the same phase)
# baseline (speedup 1.0000x reference)
.LBB0_417:
	s_setprio 0
	v_and_b32_e32 v134, 16, v153
	v_lshrrev_b32_e32 v135, 2, v153
	v_and_or_b32 v134, v135, 8, v134
	v_mov_b64_e32 v[132:133], s[50:51]
	v_mad_u64_u32 v[132:133], s[38:39], v136, s21, v[132:133]
	v_mad_i32_i24 v133, v137, s21, v133
	v_lshl_add_u64 v[132:133], v[132:133], 0, s[30:31]
	v_lshlrev_b32_e32 v134, 1, v134
	v_mov_b32_e32 v135, 0
	v_lshl_add_u64 v[132:133], v[132:133], 0, v[134:135]
	v_lshlrev_b32_e32 v134, 4, v152
	global_load_dwordx4 v[84:87], v[132:133], off offset:1024
	global_load_dwordx4 v[100:103], v134, s[42:43]
	global_load_dwordx4 v[116:119], v134, s[42:43] offset:64
	global_load_dwordx4 v[88:91], v[132:133], off offset:1088
	global_load_dwordx4 v[104:107], v134, s[42:43] offset:128
	global_load_dwordx4 v[120:123], v134, s[42:43] offset:192
	global_load_dwordx4 v[92:95], v[132:133], off offset:1152
	global_load_dwordx4 v[108:111], v134, s[42:43] offset:256
	global_load_dwordx4 v[124:127], v134, s[42:43] offset:320
	global_load_dwordx4 v[96:99], v[132:133], off offset:1216
	global_load_dwordx4 v[112:115], v134, s[42:43] offset:384
	global_load_dwordx4 v[128:131], v134, s[42:43] offset:448
	ds_bpermute_b32 v0, v148, v162
	s_waitcnt lgkmcnt(0)
	v_add_f32_e32 v0, v162, v0
	ds_bpermute_b32 v2, v149, v0
	s_waitcnt lgkmcnt(0)
	v_add_f32_e32 v0, v0, v2
	ds_bpermute_b32 v2, v148, v160
	s_waitcnt lgkmcnt(0)
	v_add_f32_e32 v2, v160, v2
	ds_bpermute_b32 v3, v149, v2
	s_waitcnt lgkmcnt(0)
	v_add_f32_e32 v2, v2, v3
	v_div_scale_f32 v3, s[38:39], v0, v0, 1.0
	v_rcp_f32_e32 v28, v3
	s_nop 0
	v_fma_f32 v29, -v3, v28, 1.0
	v_fmac_f32_e32 v28, v29, v28
	v_div_scale_f32 v29, vcc, 1.0, v0, 1.0
	v_mul_f32_e32 v30, v29, v28
	v_fma_f32 v31, -v3, v30, v29
	v_fmac_f32_e32 v30, v31, v28
	v_fma_f32 v3, -v3, v30, v29
	v_div_fmas_f32 v3, v3, v28, v30
	v_div_fixup_f32 v0, v3, v0, 1.0
	v_div_scale_f32 v3, s[38:39], v2, v2, v150
	v_rcp_f32_e32 v28, v3
	s_nop 0
	v_fma_f32 v29, -v3, v28, 1.0
	v_fmac_f32_e32 v28, v29, v28
	v_div_scale_f32 v29, vcc, v150, v2, v150
	v_mul_f32_e32 v30, v29, v28
	v_fma_f32 v31, -v3, v30, v29
	v_fmac_f32_e32 v30, v31, v28
	v_fma_f32 v3, -v3, v30, v29
	v_div_fmas_f32 v3, v3, v28, v30
	v_div_fixup_f32 v2, v3, v2, v150
	v_pk_mul_f32 v[28:29], v[80:81], v[2:3] op_sel_hi:[1,0]
	v_pk_mul_f32 v[30:31], v[82:83], v[2:3] op_sel_hi:[1,0]
	v_pk_fma_f32 v[38:39], v[72:73], v[0:1], v[28:29] op_sel_hi:[1,0,1] neg_lo:[0,0,1] neg_hi:[0,0,1]
	v_pk_mul_f32 v[28:29], v[76:77], v[2:3] op_sel_hi:[1,0]
	v_pk_fma_f32 v[36:37], v[74:75], v[0:1], v[30:31] op_sel_hi:[1,0,1] neg_lo:[0,0,1] neg_hi:[0,0,1]
	v_pk_mul_f32 v[30:31], v[78:79], v[2:3] op_sel_hi:[1,0]
	v_pk_fma_f32 v[42:43], v[68:69], v[0:1], v[28:29] op_sel_hi:[1,0,1] neg_lo:[0,0,1] neg_hi:[0,0,1]
	v_pk_fma_f32 v[40:41], v[70:71], v[0:1], v[30:31] op_sel_hi:[1,0,1] neg_lo:[0,0,1] neg_hi:[0,0,1]
	v_mov_b32_e32 v30, v39
	v_mov_b32_e32 v31, v43
	v_mov_b32_e32 v28, v38
	v_mov_b32_e32 v29, v42
	v_pk_mul_f32 v[30:31], v[30:31], v[30:31]
	v_mov_b32_e32 v32, v37
	v_mov_b32_e32 v33, v41
	v_pk_fma_f32 v[28:29], v[28:29], v[28:29], v[30:31]
	v_mov_b32_e32 v30, v36
	v_mov_b32_e32 v31, v40
	v_pk_mul_f32 v[32:33], v[32:33], v[32:33]
	v_pk_mul_f32 v[44:45], v[44:45], v[2:3] op_sel_hi:[1,0]
	v_pk_fma_f32 v[30:31], v[30:31], v[30:31], v[32:33]
	v_pk_mul_f32 v[46:47], v[46:47], v[2:3] op_sel_hi:[1,0]
	v_pk_add_f32 v[28:29], v[28:29], v[30:31]
	v_pk_mul_f32 v[30:31], v[66:67], v[2:3] op_sel_hi:[1,0]
	v_pk_add_f32 v[68:69], v[28:29], v[28:29] op_sel_hi:[0,1]
	v_pk_mul_f32 v[28:29], v[64:65], v[2:3] op_sel_hi:[1,0]
	v_pk_fma_f32 v[30:31], v[62:63], v[0:1], v[30:31] op_sel_hi:[1,0,1] neg_lo:[0,0,1] neg_hi:[0,0,1]
	v_pk_fma_f32 v[28:29], v[60:61], v[0:1], v[28:29] op_sel_hi:[1,0,1] neg_lo:[0,0,1] neg_hi:[0,0,1]
	v_pk_mul_f32 v[32:33], v[30:31], v[30:31]
	v_pk_mul_f32 v[34:35], v[28:29], v[28:29]
	v_pk_fma_f32 v[26:27], v[26:27], v[0:1], v[46:47] op_sel_hi:[1,0,1] neg_lo:[0,0,1] neg_hi:[0,0,1]
	v_pk_mov_b32 v[60:61], v[34:35], v[32:33] op_sel:[1,0]
	v_mov_b32_e32 v35, v33
	v_pk_add_f32 v[32:33], v[60:61], v[34:35]
	v_pk_mul_f32 v[34:35], v[56:57], v[2:3] op_sel_hi:[1,0]
	v_pk_add_f32 v[60:61], v[32:33], v[32:33] op_sel_hi:[0,1]
	v_pk_fma_f32 v[34:35], v[48:49], v[0:1], v[34:35] op_sel_hi:[1,0,1] neg_lo:[0,0,1] neg_hi:[0,0,1]
	v_pk_mul_f32 v[32:33], v[58:59], v[2:3] op_sel_hi:[1,0]
	v_mul_f32_e32 v48, v34, v34
	v_pk_fma_f32 v[32:33], v[50:51], v[0:1], v[32:33] op_sel_hi:[1,0,1] neg_lo:[0,0,1] neg_hi:[0,0,1]
	v_pk_fma_f32 v[48:49], v[34:35], v[34:35], v[48:49] op_sel_hi:[1,1,0]
	v_pk_fma_f32 v[24:25], v[24:25], v[0:1], v[44:45] op_sel_hi:[1,0,1] neg_lo:[0,0,1] neg_hi:[0,0,1]
	v_mul_f32_e32 v48, v32, v32
	v_pk_fma_f32 v[50:51], v[32:33], v[32:33], v[48:49] op_sel_hi:[1,1,0]
	v_pk_mul_f32 v[22:23], v[22:23], v[2:3] op_sel_hi:[1,0]
	v_pk_mul_f32 v[20:21], v[20:21], v[2:3] op_sel_hi:[1,0]
	v_pk_mul_f32 v[12:13], v[12:13], v[2:3] op_sel_hi:[1,0]
	v_mul_f32_e32 v48, v24, v24
	v_mul_f32_e32 v50, v25, v25
	v_mul_f32_e32 v60, v26, v26
	v_mul_f32_e32 v68, v27, v27
	v_pk_fma_f32 v[16:17], v[16:17], v[0:1], v[20:21] op_sel_hi:[1,0,1] neg_lo:[0,0,1] neg_hi:[0,0,1]
	v_pk_fma_f32 v[20:21], v[18:19], v[0:1], v[22:23] op_sel_hi:[1,0,1] neg_lo:[0,0,1] neg_hi:[0,0,1]
	v_pk_mul_f32 v[14:15], v[14:15], v[2:3] op_sel_hi:[1,0]
	v_pk_fma_f32 v[8:9], v[8:9], v[0:1], v[12:13] op_sel_hi:[1,0,1] neg_lo:[0,0,1] neg_hi:[0,0,1]
	v_pk_add_f32 v[44:45], v[48:49], v[50:51]
	v_pk_add_f32 v[46:47], v[60:61], v[68:69]
	v_pk_mul_f32 v[18:19], v[20:21], v[20:21]
	v_pk_mul_f32 v[22:23], v[16:17], v[16:17]
	v_pk_fma_f32 v[10:11], v[10:11], v[0:1], v[14:15] op_sel_hi:[1,0,1] neg_lo:[0,0,1] neg_hi:[0,0,1]
	v_mul_f32_e32 v12, v8, v8
	v_pk_add_f32 v[44:45], v[44:45], v[46:47]
	v_pk_mov_b32 v[46:47], v[22:23], v[18:19] op_sel:[1,0]
	v_mov_b32_e32 v23, v19
	v_pk_fma_f32 v[14:15], v[8:9], v[8:9], v[12:13] op_sel_hi:[1,1,0]
	v_mul_f32_e32 v12, v10, v10
	v_pk_add_f32 v[18:19], v[46:47], v[22:23]
	v_pk_fma_f32 v[22:23], v[10:11], v[10:11], v[12:13] op_sel_hi:[1,1,0]
	v_pk_mul_f32 v[12:13], v[52:53], v[2:3] op_sel_hi:[1,0]
	v_pk_mul_f32 v[2:3], v[54:55], v[2:3] op_sel_hi:[1,0]
	v_pk_add_f32 v[44:45], v[44:45], v[44:45] op_sel_hi:[0,1]
	v_pk_add_f32 v[18:19], v[18:19], v[18:19] op_sel_hi:[0,1]
	v_pk_fma_f32 v[6:7], v[6:7], v[0:1], v[2:3] op_sel_hi:[1,0,1] neg_lo:[0,0,1] neg_hi:[0,0,1]
	v_pk_fma_f32 v[12:13], v[4:5], v[0:1], v[12:13] op_sel_hi:[1,0,1] neg_lo:[0,0,1] neg_hi:[0,0,1]
	v_mul_f32_e32 v18, v6, v6
	v_mul_f32_e32 v14, v12, v12
	v_mul_f32_e32 v22, v13, v13
	v_mul_f32_e32 v44, v7, v7
	v_pk_add_f32 v[2:3], v[14:15], v[22:23]
	v_pk_add_f32 v[4:5], v[18:19], v[44:45]
	s_nop 0
	v_pk_add_f32 v[2:3], v[2:3], v[4:5]
	s_nop 0
	v_add_f32_e32 v0, v2, v3
	ds_bpermute_b32 v2, v148, v0
	s_waitcnt lgkmcnt(0)
	v_add_f32_e32 v0, v0, v2
	ds_bpermute_b32 v2, v149, v0
	s_waitcnt lgkmcnt(0)
	v_add_f32_e32 v0, v0, v2
	v_fmamk_f32 v0, v0, 0x3c000000, v227
	v_cmp_gt_f32_e32 vcc, s7, v0
	v_mul_f32_e32 v2, 0x4f800000, v0
	s_nop 0
	v_cndmask_b32_e32 v0, v0, v2, vcc
	v_sqrt_f32_e32 v2, v0
	s_nop 0
	v_add_u32_e32 v3, -1, v2
	v_fma_f32 v4, -v3, v2, v0
	v_cmp_ge_f32_e64 s[38:39], 0, v4
	v_add_u32_e32 v4, 1, v2
	s_nop 0
	v_cndmask_b32_e64 v3, v2, v3, s[38:39]
	v_fma_f32 v2, -v4, v2, v0
	v_cmp_lt_f32_e64 s[38:39], 0, v2
	s_nop 1
	v_cndmask_b32_e64 v2, v3, v4, s[38:39]
	v_mul_f32_e32 v3, 0x37800000, v2
	v_cndmask_b32_e32 v2, v2, v3, vcc
	v_cmp_class_f32_e32 vcc, v0, v228
	s_nop 1
	v_cndmask_b32_e32 v0, v2, v0, vcc
	v_div_scale_f32 v2, s[38:39], v0, v0, v151
	v_rcp_f32_e32 v3, v2
	s_nop 0
	v_fma_f32 v4, -v2, v3, 1.0
	v_fmac_f32_e32 v3, v4, v3
	v_div_scale_f32 v4, vcc, v151, v0, v151
	v_mul_f32_e32 v5, v4, v3
	v_fma_f32 v14, -v2, v5, v4
	v_fmac_f32_e32 v5, v14, v3
	v_fma_f32 v2, -v2, v5, v4
	v_div_fmas_f32 v2, v2, v3, v5
	v_div_fixup_f32 v18, v2, v0, v151
	v_and_b32_e32 v0, 16, v153
	v_lshrrev_b32_e32 v2, 2, v153
	v_and_or_b32 v0, v2, 8, v0
	v_mov_b64_e32 v[2:3], s[50:51]
	v_mad_u64_u32 v[2:3], s[38:39], v136, s21, v[2:3]
	v_mad_i32_i24 v3, v137, s21, v3
	v_lshl_add_u64 v[2:3], v[2:3], 0, s[30:31]
	v_lshlrev_b32_e32 v0, 1, v0
	v_lshl_add_u64 v[22:23], v[2:3], 0, v[0:1]
	v_lshl_add_u64 v[14:15], v[138:139], 0, v[0:1]
	v_lshlrev_b32_e32 v0, 4, v152
	s_waitcnt vmcnt(0)
	v_mov_b32_e32 v2, v84
	v_mov_b32_e32 v3, v85
	v_mov_b32_e32 v4, v86
	v_mov_b32_e32 v5, v87
	s_nop 1
	v_mov_b32_e32 v44, v100
	v_mov_b32_e32 v45, v101
	v_mov_b32_e32 v46, v102
	v_mov_b32_e32 v47, v103
	s_nop 1
	v_mov_b32_e32 v48, v116
	v_mov_b32_e32 v49, v117
	v_mov_b32_e32 v50, v118
	v_mov_b32_e32 v51, v119
	v_pk_mul_f32 v[38:39], v[38:39], v[18:19] op_sel_hi:[1,0]
	v_pk_mul_f32 v[42:43], v[42:43], v[18:19] op_sel_hi:[1,0]
	v_pk_mul_f32 v[36:37], v[36:37], v[18:19] op_sel_hi:[1,0]
	v_pk_mul_f32 v[40:41], v[40:41], v[18:19] op_sel_hi:[1,0]
	v_mov_b32_e32 v153, v224
	s_lshl_b32 s39, s16, 7
	v_lshlrev_b32_e32 v19, 16, v2
	v_pk_mul_f32 v[38:39], v[44:45], v[38:39]
	v_pk_mul_f32 v[42:43], v[48:49], v[42:43]
	v_and_b32_e32 v2, 0xffff0000, v2
	s_nop 0
	v_permlane16_swap_b32_e32 v38, v42
	v_permlane16_swap_b32_e32 v39, v43
	v_pk_mul_f32 v[36:37], v[46:47], v[36:37]
	v_pk_mul_f32 v[40:41], v[50:51], v[40:41]
	v_mul_f32_e32 v19, v19, v38
	v_mul_f32_e32 v2, v2, v39
	v_permlane16_swap_b32_e32 v36, v40
	v_permlane16_swap_b32_e32 v37, v41
	v_cvt_pk_bf16_f32 v2, v19, v2
	v_lshlrev_b32_e32 v19, 16, v3
	v_and_b32_e32 v3, 0xffff0000, v3
	v_mul_f32_e32 v19, v19, v36
	v_mul_f32_e32 v3, v3, v37
	v_cvt_pk_bf16_f32 v3, v19, v3
	v_lshlrev_b32_e32 v19, 16, v4
	v_and_b32_e32 v4, 0xffff0000, v4
	v_mul_f32_e32 v19, v19, v42
	v_mul_f32_e32 v4, v4, v43
	v_cvt_pk_bf16_f32 v4, v19, v4
	v_lshlrev_b32_e32 v19, 16, v5
	v_and_b32_e32 v5, 0xffff0000, v5
	v_mul_f32_e32 v5, v5, v41
	v_mul_f32_e32 v19, v19, v40
	v_cvt_pk_bf16_f32 v5, v19, v5
	global_store_dwordx4 v[14:15], v[2:5], off
	s_nop 1
	v_mov_b32_e32 v2, v88
	v_mov_b32_e32 v3, v89
	v_mov_b32_e32 v4, v90
	v_mov_b32_e32 v5, v91
	s_nop 0
	s_nop 1
	v_mov_b32_e32 v36, v104
	v_mov_b32_e32 v37, v105
	v_mov_b32_e32 v38, v106
	v_mov_b32_e32 v39, v107
	s_nop 1
	v_mov_b32_e32 v40, v120
	v_mov_b32_e32 v41, v121
	v_mov_b32_e32 v42, v122
	v_mov_b32_e32 v43, v123
	v_pk_mul_f32 v[28:29], v[28:29], v[18:19] op_sel_hi:[1,0]
	v_pk_mul_f32 v[34:35], v[34:35], v[18:19] op_sel_hi:[1,0]
	v_pk_mul_f32 v[30:31], v[30:31], v[18:19] op_sel_hi:[1,0]
	v_pk_mul_f32 v[32:33], v[32:33], v[18:19] op_sel_hi:[1,0]
	v_lshlrev_b32_e32 v19, 16, v2
	v_pk_mul_f32 v[28:29], v[36:37], v[28:29]
	v_pk_mul_f32 v[34:35], v[40:41], v[34:35]
	v_and_b32_e32 v2, 0xffff0000, v2
	s_nop 0
	v_permlane16_swap_b32_e32 v28, v34
	v_permlane16_swap_b32_e32 v29, v35
	v_pk_mul_f32 v[30:31], v[38:39], v[30:31]
	v_pk_mul_f32 v[32:33], v[42:43], v[32:33]
	v_mul_f32_e32 v19, v19, v28
	v_mul_f32_e32 v2, v2, v29
	v_permlane16_swap_b32_e32 v30, v32
	v_permlane16_swap_b32_e32 v31, v33
	v_cvt_pk_bf16_f32 v2, v19, v2
	v_lshlrev_b32_e32 v19, 16, v3
	v_and_b32_e32 v3, 0xffff0000, v3
	v_mul_f32_e32 v19, v19, v30
	v_mul_f32_e32 v3, v3, v31
	v_cvt_pk_bf16_f32 v3, v19, v3
	v_lshlrev_b32_e32 v19, 16, v4
	v_and_b32_e32 v4, 0xffff0000, v4
	v_mul_f32_e32 v19, v19, v34
	v_mul_f32_e32 v4, v4, v35
	v_cvt_pk_bf16_f32 v4, v19, v4
	v_lshlrev_b32_e32 v19, 16, v5
	v_and_b32_e32 v5, 0xffff0000, v5
	v_mul_f32_e32 v5, v5, v33
	v_mul_f32_e32 v19, v19, v32
	v_cvt_pk_bf16_f32 v5, v19, v5
	global_store_dwordx4 v[14:15], v[2:5], off offset:64
	s_nop 1
	v_mov_b32_e32 v2, v92
	v_mov_b32_e32 v3, v93
	v_mov_b32_e32 v4, v94
	v_mov_b32_e32 v5, v95
	s_nop 0
	s_nop 1
	v_mov_b32_e32 v28, v108
	v_mov_b32_e32 v29, v109
	v_mov_b32_e32 v30, v110
	v_mov_b32_e32 v31, v111
	s_nop 1
	v_mov_b32_e32 v32, v124
	v_mov_b32_e32 v33, v125
	v_mov_b32_e32 v34, v126
	v_mov_b32_e32 v35, v127
	v_pk_mul_f32 v[24:25], v[24:25], v[18:19] op_sel_hi:[1,0]
	v_pk_mul_f32 v[16:17], v[16:17], v[18:19] op_sel_hi:[1,0]
	v_pk_mul_f32 v[26:27], v[26:27], v[18:19] op_sel_hi:[1,0]
	v_pk_mul_f32 v[20:21], v[20:21], v[18:19] op_sel_hi:[1,0]
	v_lshlrev_b32_e32 v19, 16, v2
	v_pk_mul_f32 v[24:25], v[24:25], v[28:29]
	v_pk_mul_f32 v[16:17], v[16:17], v[32:33]
	v_and_b32_e32 v2, 0xffff0000, v2
	s_nop 0
	v_permlane16_swap_b32_e32 v24, v16
	v_permlane16_swap_b32_e32 v25, v17
	v_pk_mul_f32 v[26:27], v[26:27], v[30:31]
	v_pk_mul_f32 v[20:21], v[20:21], v[34:35]
	v_mul_f32_e32 v19, v19, v24
	v_mul_f32_e32 v2, v2, v25
	v_permlane16_swap_b32_e32 v26, v20
	v_permlane16_swap_b32_e32 v27, v21
	v_cvt_pk_bf16_f32 v2, v19, v2
	v_lshlrev_b32_e32 v19, 16, v3
	v_and_b32_e32 v3, 0xffff0000, v3
	v_mul_f32_e32 v19, v19, v26
	v_mul_f32_e32 v3, v3, v27
	v_cvt_pk_bf16_f32 v3, v19, v3
	v_lshlrev_b32_e32 v19, 16, v4
	v_and_b32_e32 v4, 0xffff0000, v4
	v_mul_f32_e32 v16, v19, v16
	v_mul_f32_e32 v4, v4, v17
	v_cvt_pk_bf16_f32 v4, v16, v4
	v_lshlrev_b32_e32 v16, 16, v5
	v_and_b32_e32 v5, 0xffff0000, v5
	v_mul_f32_e32 v5, v5, v21
	v_mul_f32_e32 v16, v16, v20
	v_cvt_pk_bf16_f32 v5, v16, v5
	global_store_dwordx4 v[14:15], v[2:5], off offset:128
	s_nop 1
	v_mov_b32_e32 v2, v96
	v_mov_b32_e32 v3, v97
	v_mov_b32_e32 v4, v98
	v_mov_b32_e32 v5, v99
	s_nop 0
	s_nop 1
	v_mov_b32_e32 v20, v112
	v_mov_b32_e32 v21, v113
	v_mov_b32_e32 v22, v114
	v_mov_b32_e32 v23, v115
	s_nop 1
	v_mov_b32_e32 v24, v128
	v_mov_b32_e32 v25, v129
	v_mov_b32_e32 v26, v130
	v_mov_b32_e32 v27, v131
	v_pk_mul_f32 v[8:9], v[8:9], v[18:19] op_sel_hi:[1,0]
	v_pk_mul_f32 v[12:13], v[12:13], v[18:19] op_sel_hi:[1,0]
	v_pk_mul_f32 v[10:11], v[10:11], v[18:19] op_sel_hi:[1,0]
	v_pk_mul_f32 v[6:7], v[6:7], v[18:19] op_sel_hi:[1,0]
	v_lshlrev_b32_e32 v0, 16, v2
	v_pk_mul_f32 v[8:9], v[8:9], v[20:21]
	v_pk_mul_f32 v[12:13], v[12:13], v[24:25]
	v_and_b32_e32 v2, 0xffff0000, v2
	s_nop 0
	v_permlane16_swap_b32_e32 v8, v12
	v_permlane16_swap_b32_e32 v9, v13
	v_pk_mul_f32 v[10:11], v[10:11], v[22:23]
	v_pk_mul_f32 v[6:7], v[6:7], v[26:27]
	v_mul_f32_e32 v0, v0, v8
	v_mul_f32_e32 v2, v2, v9
	v_permlane16_swap_b32_e32 v10, v6
	v_permlane16_swap_b32_e32 v11, v7
	v_cvt_pk_bf16_f32 v2, v0, v2
	v_lshlrev_b32_e32 v0, 16, v3
	v_and_b32_e32 v3, 0xffff0000, v3
	v_mul_f32_e32 v0, v0, v10
	v_mul_f32_e32 v3, v3, v11
	v_cvt_pk_bf16_f32 v3, v0, v3
	v_lshlrev_b32_e32 v0, 16, v4
	v_and_b32_e32 v4, 0xffff0000, v4
	v_mul_f32_e32 v0, v0, v12
	v_mul_f32_e32 v4, v4, v13
	v_cvt_pk_bf16_f32 v4, v0, v4
	v_lshlrev_b32_e32 v0, 16, v5
	v_and_b32_e32 v5, 0xffff0000, v5
	v_mul_f32_e32 v5, v5, v7
	v_mul_f32_e32 v0, v0, v6
	v_cvt_pk_bf16_f32 v5, v0, v5
	global_store_dwordx4 v[14:15], v[2:5], off offset:192
	s_nop 0
	v_readfirstlane_b32 s38, v153
	s_ashr_i32 s38, s38, 6
	s_lshl_b32 s62, s38, 4
	v_and_b32_e32 v2, 15, v153
	s_add_i32 s62, s62, s39
	v_or_b32_e32 v4, s62, v2
	v_ashrrev_i32_e32 v5, 31, v4
	v_lshl_add_u64 v[136:137], s[44:45], 0, v[4:5]
	v_mov_b64_e32 v[4:5], s[28:29]
	v_mad_u64_u32 v[4:5], s[62:63], v136, s23, v[4:5]
	v_mad_i32_i24 v5, v137, s23, v5
	v_lshl_add_u64 v[138:139], v[4:5], 0, s[30:31]
	v_and_b32_e32 v0, 48, v153
	v_lshl_add_u64 v[4:5], v[138:139], 0, v[0:1]
	global_load_dwordx4 v[36:39], v[4:5], off
	global_load_dwordx4 v[40:43], v[4:5], off offset:64
	global_load_dwordx4 v[44:47], v[4:5], off offset:128
	global_load_dwordx4 v[52:55], v[4:5], off offset:192
	s_cmp_lt_i32 s38, 4
	s_cbranch_scc1 .LBB0_419
	s_setprio 0
